# stack15 + Q part of the QKV projections block-permuted: QKV GEMM epilogue quads store whole 64-byte lines on Q column tiles (K/V tiles plain), attention Q-fragment loads follow the permutation
# speedup vs baseline: 1.0240x; 1.0050x over previous
.LBB0_239:
	s_or_b64 exec, exec, s[62:63]
	s_add_i32 s0, s98, s18
	s_lshl_b32 s62, s0, 6
	s_ashr_i32 s63, s62, 31
	s_lshl_b64 s[64:65], s[62:63], 1
	s_add_u32 s16, s16, s64
	s_addc_u32 s17, s17, s65
	s_ashr_i32 s1, s0, 31
	s_lshl_b64 s[0:1], s[0:1], 2
	s_add_u32 s62, s2, s0
	s_addc_u32 s63, s3, s1
	s_or_b32 s66, s72, s90
	v_mov_b32_e32 v91, v1
	v_or_b32_e32 v0, s66, v87
	s_waitcnt vmcnt(0)
	v_mov_b64_e32 v[2:3], s[58:59]
	v_lshl_add_u64 v[98:99], s[16:17], 0, v[90:91]
	v_mad_u64_u32 v[94:95], s[16:17], v0, s93, v[2:3]
	v_lshrrev_b32_e32 v216, 5, v158
	v_and_or_b32 v217, v94, -4, v216
	v_mad_u64_u32 v[2:3], s[16:17], v217, s19, 0
	v_mov_b32_e32 v0, v3
	v_mad_u64_u32 v[4:5], s[16:17], v95, s19, v[0:1]
	v_mov_b32_e32 v3, v4
	v_lshl_add_u64 v[2:3], v[2:3], 1, v[98:99]
	v_and_b32_e32 v218, 3, v94
	v_sub_u32_e32 v218, v218, v216
	v_lshlrev_b32_e32 v218, 4, v218
	v_ashrrev_i32_e32 v219, 31, v218
	v_lshl_add_u64 v[2:3], v[2:3], 0, v[218:219]
	v_lshlrev_b32_e64 v220, 2, s19
	v_mov_b32_e32 v221, 0
	v_lshl_add_u64 v[220:221], v[2:3], 0, v[220:221]
	s_waitcnt lgkmcnt(0)
	s_barrier
	global_load_dwordx4 v[64:67], v[2:3], off
	global_load_dwordx4 v[68:71], v[220:221], off
	global_load_dwordx4 v[72:75], v[2:3], off offset:64
	global_load_dwordx4 v[76:79], v[220:221], off offset:64
	v_cndmask_b32_e64 v0, 0, 1, s[52:53]
	v_cmp_ne_u32_e64 s[16:17], 1, v0
	s_andn2_b64 vcc, exec, s[52:53]
	s_cbranch_vccnz .LBB0_241
	global_load_dword v0, v1, s[62:63]
	v_mov_b32_e32 v138, v89
	s_waitcnt vmcnt(0)
	v_mul_f32_e32 v93, 0x3fb8aa3b, v0
	s_branch .LBB0_242

.LBB0_252:
	s_or_b64 exec, exec, s[60:61]
	s_or_b32 s60, s72, s91
	v_or_b32_e32 v0, s60, v87
	v_mov_b64_e32 v[2:3], s[58:59]
	v_mad_u64_u32 v[94:95], s[58:59], v0, s93, v[2:3]
	v_lshrrev_b32_e32 v216, 5, v158
	v_and_or_b32 v217, v94, -4, v216
	v_mad_u64_u32 v[2:3], s[58:59], v217, s19, 0
	v_mov_b32_e32 v0, v3
	v_mad_u64_u32 v[4:5], s[58:59], v95, s19, v[0:1]
	v_mov_b32_e32 v3, v4
	v_lshl_add_u64 v[2:3], v[2:3], 1, v[98:99]
	v_and_b32_e32 v218, 3, v94
	v_sub_u32_e32 v218, v218, v216
	v_lshlrev_b32_e32 v218, 4, v218
	v_ashrrev_i32_e32 v219, 31, v218
	v_lshl_add_u64 v[2:3], v[2:3], 0, v[218:219]
	v_lshlrev_b32_e64 v220, 2, s19
	v_mov_b32_e32 v221, 0
	v_lshl_add_u64 v[220:221], v[2:3], 0, v[220:221]
	global_load_dwordx4 v[64:67], v[2:3], off
	global_load_dwordx4 v[68:71], v[220:221], off
	global_load_dwordx4 v[72:75], v[2:3], off offset:64
	global_load_dwordx4 v[76:79], v[220:221], off offset:64
	s_and_b64 vcc, exec, s[16:17]
	s_cbranch_vccnz .LBB0_254
	global_load_dword v0, v1, s[62:63]
	v_mov_b32_e32 v93, v89
	s_waitcnt vmcnt(0)
	v_mul_f32_e32 v138, 0x3fb8aa3b, v0
	s_branch .LBB0_255

.LBB0_422:
	s_mov_b32 s100, 0xf3cf
	s_lshr_b32 s100, s100, s63
	s_bitcmp1_b32 s100, 0
	s_cselect_b64 vcc, -1, 0
	v_and_b32_e32 v234, 15, v150
	v_bfe_u32 v235, v150, 4, 2
	v_lshrrev_b32_e32 v236, 2, v234
	v_and_b32_e32 v234, 3, v234
	v_lshl_or_b32 v235, v236, 2, v235
	v_lshlrev_b32_e32 v234, 3, v234
	v_and_or_b32 v232, v142, -16, v235
	v_lshrrev_b32_e32 v233, 5, v144
	v_lshl_or_b32 v233, v233, 5, v234
	v_cndmask_b32_e32 v232, v142, v232, vcc
	v_cndmask_b32_e32 v233, v144, v233, vcc
	ds_read_b128 v[160:163], v147
	v_lshl_add_u32 v148, s62, 8, v232
	v_ashrrev_i32_e32 v149, 31, v148
	v_mul_lo_u32 v149, s68, v149
	v_mul_lo_u32 v159, s69, v148
	s_waitcnt lgkmcnt(0)
	v_mov_b32_e32 v166, v161
	v_mov_b32_e32 v167, v162
	v_mov_b32_e32 v161, v163
	v_mad_u64_u32 v[164:165], s[16:17], s68, v148, 0
	v_pk_add_f32 v[160:161], v[166:167], v[160:161]
	v_add3_u32 v165, v165, v149, v159
	v_add_f32_e32 v159, v160, v161
	v_fmamk_f32 v159, v159, 0x3a800000, v155
	v_rsq_f32_e32 v160, v159
	v_lshl_or_b32 v140, s63, 8, v233
	v_ashrrev_i32_e32 v141, 31, v140
	v_lshl_add_u64 v[162:163], v[164:165], 1, s[78:79]
	v_lshlrev_b64 v[140:141], 1, v[140:141]
	v_lshl_add_u64 v[162:163], v[162:163], 0, v[140:141]
	v_pk_mul_f32 v[128:129], v[128:129], v[160:161] op_sel_hi:[1,0]
	v_pk_mul_f32 v[126:127], v[126:127], v[160:161] op_sel_hi:[1,0]
	v_pk_mul_f32 v[164:165], v[124:125], v[160:161] op_sel_hi:[1,0]
	v_pk_mul_f32 v[124:125], v[122:123], v[160:161] op_sel_hi:[1,0]
	v_cvt_pk_bf16_f32 v122, v126, v127
	v_cvt_pk_bf16_f32 v123, v128, v129
	v_pk_mul_f32 v[120:121], v[120:121], v[160:161] op_sel_hi:[1,0]
	v_cvt_pk_bf16_f32 v124, v124, v125
	v_cvt_pk_bf16_f32 v125, v164, v165
	global_store_dwordx4 v[162:163], v[122:125], off
	v_pk_mul_f32 v[118:119], v[118:119], v[160:161] op_sel_hi:[1,0]
	s_and_b64 vcc, exec, s[6:7]
	v_pk_mul_f32 v[122:123], v[116:117], v[160:161] op_sel_hi:[1,0]
	v_pk_mul_f32 v[116:117], v[114:115], v[160:161] op_sel_hi:[1,0]
	v_cvt_pk_bf16_f32 v114, v118, v119
	v_cvt_pk_bf16_f32 v115, v120, v121
	v_or_b32_e32 v118, 16, v148
	v_cvt_pk_bf16_f32 v116, v116, v117
	v_cvt_pk_bf16_f32 v117, v122, v123
	global_store_dwordx4 v[162:163], v[114:117], off offset:256
	ds_read_b128 v[114:117], v147 offset:256
	v_mul_lo_u32 v122, s69, v118
	v_mad_u64_u32 v[118:119], s[16:17], s68, v118, 0
	v_add3_u32 v119, v119, v149, v122
	s_waitcnt lgkmcnt(0)
	v_mov_b32_e32 v120, v115
	v_mov_b32_e32 v121, v116
	v_mov_b32_e32 v115, v117
	v_pk_add_f32 v[114:115], v[120:121], v[114:115]
	v_lshl_add_u64 v[116:117], v[118:119], 1, s[78:79]
	v_add_f32_e32 v114, v114, v115
	v_fmamk_f32 v114, v114, 0x3a800000, v155
	v_rsq_f32_e32 v114, v114
	v_lshl_add_u64 v[116:117], v[116:117], 0, v[140:141]
	s_mov_b64 s[6:7], -1
	v_pk_mul_f32 v[112:113], v[112:113], v[114:115] op_sel_hi:[1,0]
	v_pk_mul_f32 v[110:111], v[110:111], v[114:115] op_sel_hi:[1,0]
	v_pk_mul_f32 v[118:119], v[108:109], v[114:115] op_sel_hi:[1,0]
	v_pk_mul_f32 v[108:109], v[106:107], v[114:115] op_sel_hi:[1,0]
	v_cvt_pk_bf16_f32 v106, v110, v111
	v_cvt_pk_bf16_f32 v107, v112, v113
	v_pk_mul_f32 v[104:105], v[104:105], v[114:115] op_sel_hi:[1,0]
	v_cvt_pk_bf16_f32 v108, v108, v109
	v_cvt_pk_bf16_f32 v109, v118, v119
	global_store_dwordx4 v[116:117], v[106:109], off
	v_pk_mul_f32 v[102:103], v[102:103], v[114:115] op_sel_hi:[1,0]
	s_nop 0
	v_pk_mul_f32 v[106:107], v[100:101], v[114:115] op_sel_hi:[1,0]
	v_pk_mul_f32 v[100:101], v[98:99], v[114:115] op_sel_hi:[1,0]
	v_cvt_pk_bf16_f32 v98, v102, v103
	v_cvt_pk_bf16_f32 v99, v104, v105
	v_or_b32_e32 v102, 32, v148
	v_cvt_pk_bf16_f32 v100, v100, v101
	v_cvt_pk_bf16_f32 v101, v106, v107
	global_store_dwordx4 v[116:117], v[98:101], off offset:256
	ds_read_b128 v[98:101], v147 offset:512
	v_mul_lo_u32 v106, s69, v102
	v_mad_u64_u32 v[102:103], s[16:17], s68, v102, 0
	v_add3_u32 v103, v103, v149, v106
	s_waitcnt lgkmcnt(0)
	v_mov_b32_e32 v104, v99
	v_mov_b32_e32 v105, v100
	v_mov_b32_e32 v99, v101
	v_pk_add_f32 v[98:99], v[104:105], v[98:99]
	v_lshl_add_u64 v[100:101], v[102:103], 1, s[78:79]
	v_add_f32_e32 v98, v98, v99
	v_fmamk_f32 v98, v98, 0x3a800000, v155
	v_rsq_f32_e32 v98, v98
	v_lshl_add_u64 v[100:101], v[100:101], 0, v[140:141]
	v_pk_mul_f32 v[96:97], v[96:97], v[98:99] op_sel_hi:[1,0]
	v_pk_mul_f32 v[94:95], v[94:95], v[98:99] op_sel_hi:[1,0]
	v_pk_mul_f32 v[102:103], v[92:93], v[98:99] op_sel_hi:[1,0]
	v_pk_mul_f32 v[92:93], v[90:91], v[98:99] op_sel_hi:[1,0]
	v_cvt_pk_bf16_f32 v90, v94, v95
	v_cvt_pk_bf16_f32 v91, v96, v97
	v_pk_mul_f32 v[88:89], v[88:89], v[98:99] op_sel_hi:[1,0]
	v_cvt_pk_bf16_f32 v92, v92, v93
	v_cvt_pk_bf16_f32 v93, v102, v103
	global_store_dwordx4 v[100:101], v[90:93], off
	v_pk_mul_f32 v[86:87], v[86:87], v[98:99] op_sel_hi:[1,0]
	s_nop 0
	v_pk_mul_f32 v[90:91], v[84:85], v[98:99] op_sel_hi:[1,0]
	v_pk_mul_f32 v[84:85], v[82:83], v[98:99] op_sel_hi:[1,0]
	v_cvt_pk_bf16_f32 v82, v86, v87
	v_cvt_pk_bf16_f32 v83, v88, v89
	v_or_b32_e32 v86, 48, v148
	v_cvt_pk_bf16_f32 v84, v84, v85
	v_cvt_pk_bf16_f32 v85, v90, v91
	global_store_dwordx4 v[100:101], v[82:85], off offset:256
	ds_read_b128 v[82:85], v147 offset:768
	v_mul_lo_u32 v90, s69, v86
	v_mad_u64_u32 v[86:87], s[16:17], s68, v86, 0
	v_add3_u32 v87, v87, v149, v90
	s_waitcnt lgkmcnt(0)
	v_mov_b32_e32 v88, v83
	v_mov_b32_e32 v89, v84
	v_mov_b32_e32 v83, v85
	v_pk_add_f32 v[82:83], v[88:89], v[82:83]
	v_lshl_add_u64 v[84:85], v[86:87], 1, s[78:79]
	v_add_f32_e32 v82, v82, v83
	v_fmamk_f32 v82, v82, 0x3a800000, v155
	v_rsq_f32_e32 v82, v82
	v_lshl_add_u64 v[84:85], v[84:85], 0, v[140:141]
	v_pk_mul_f32 v[80:81], v[80:81], v[82:83] op_sel_hi:[1,0]
	v_pk_mul_f32 v[78:79], v[78:79], v[82:83] op_sel_hi:[1,0]
	v_pk_mul_f32 v[86:87], v[76:77], v[82:83] op_sel_hi:[1,0]
	v_pk_mul_f32 v[76:77], v[74:75], v[82:83] op_sel_hi:[1,0]
	v_cvt_pk_bf16_f32 v74, v78, v79
	v_cvt_pk_bf16_f32 v75, v80, v81
	v_pk_mul_f32 v[72:73], v[72:73], v[82:83] op_sel_hi:[1,0]
	v_cvt_pk_bf16_f32 v76, v76, v77
	v_cvt_pk_bf16_f32 v77, v86, v87
	global_store_dwordx4 v[84:85], v[74:77], off
	v_pk_mul_f32 v[70:71], v[70:71], v[82:83] op_sel_hi:[1,0]
	s_nop 0
	v_pk_mul_f32 v[74:75], v[68:69], v[82:83] op_sel_hi:[1,0]
	v_pk_mul_f32 v[68:69], v[66:67], v[82:83] op_sel_hi:[1,0]
	v_cvt_pk_bf16_f32 v66, v70, v71
	v_cvt_pk_bf16_f32 v67, v72, v73
	v_add_u32_e32 v70, 0x80, v148
	v_cvt_pk_bf16_f32 v68, v68, v69
	v_cvt_pk_bf16_f32 v69, v74, v75
	global_store_dwordx4 v[84:85], v[66:69], off offset:256
	ds_read_b128 v[66:69], v147 offset:1024
	v_ashrrev_i32_e32 v71, 31, v70
	v_mul_lo_u32 v74, s68, v71
	v_mul_lo_u32 v75, s69, v70
	v_mad_u64_u32 v[70:71], s[16:17], s68, v70, 0
	s_waitcnt lgkmcnt(0)
	v_mov_b32_e32 v72, v67
	v_mov_b32_e32 v73, v68
	v_mov_b32_e32 v67, v69
	v_pk_add_f32 v[66:67], v[72:73], v[66:67]
	v_add3_u32 v71, v71, v74, v75
	v_add_f32_e32 v66, v66, v67
	v_fmamk_f32 v66, v66, 0x3a800000, v155
	v_rsq_f32_e32 v66, v66
	v_lshl_add_u64 v[68:69], v[70:71], 1, s[78:79]
	v_lshl_add_u64 v[68:69], v[68:69], 0, v[140:141]
	v_pk_mul_f32 v[64:65], v[64:65], v[66:67] op_sel_hi:[1,0]
	v_pk_mul_f32 v[62:63], v[62:63], v[66:67] op_sel_hi:[1,0]
	v_pk_mul_f32 v[70:71], v[60:61], v[66:67] op_sel_hi:[1,0]
	v_pk_mul_f32 v[60:61], v[58:59], v[66:67] op_sel_hi:[1,0]
	v_cvt_pk_bf16_f32 v58, v62, v63
	v_cvt_pk_bf16_f32 v59, v64, v65
	v_pk_mul_f32 v[56:57], v[56:57], v[66:67] op_sel_hi:[1,0]
	v_cvt_pk_bf16_f32 v60, v60, v61
	v_cvt_pk_bf16_f32 v61, v70, v71
	global_store_dwordx4 v[68:69], v[58:61], off
	v_pk_mul_f32 v[54:55], v[54:55], v[66:67] op_sel_hi:[1,0]
	s_nop 0
	v_pk_mul_f32 v[58:59], v[52:53], v[66:67] op_sel_hi:[1,0]
	v_pk_mul_f32 v[52:53], v[50:51], v[66:67] op_sel_hi:[1,0]
	v_cvt_pk_bf16_f32 v50, v54, v55
	v_cvt_pk_bf16_f32 v51, v56, v57
	v_add_u32_e32 v54, 0x90, v148
	v_cvt_pk_bf16_f32 v52, v52, v53
	v_cvt_pk_bf16_f32 v53, v58, v59
	global_store_dwordx4 v[68:69], v[50:53], off offset:256
	ds_read_b128 v[50:53], v147 offset:1280
	v_ashrrev_i32_e32 v55, 31, v54
	v_mul_lo_u32 v58, s68, v55
	v_mul_lo_u32 v59, s69, v54
	v_mad_u64_u32 v[54:55], s[16:17], s68, v54, 0
	s_waitcnt lgkmcnt(0)
	v_mov_b32_e32 v56, v51
	v_mov_b32_e32 v57, v52
	v_mov_b32_e32 v51, v53
	v_pk_add_f32 v[50:51], v[56:57], v[50:51]
	v_add3_u32 v55, v55, v58, v59
	v_add_f32_e32 v50, v50, v51
	v_fmamk_f32 v50, v50, 0x3a800000, v155
	v_rsq_f32_e32 v50, v50
	v_lshl_add_u64 v[52:53], v[54:55], 1, s[78:79]
	v_lshl_add_u64 v[52:53], v[52:53], 0, v[140:141]
	v_pk_mul_f32 v[48:49], v[48:49], v[50:51] op_sel_hi:[1,0]
	v_pk_mul_f32 v[46:47], v[46:47], v[50:51] op_sel_hi:[1,0]
	v_pk_mul_f32 v[54:55], v[44:45], v[50:51] op_sel_hi:[1,0]
	v_pk_mul_f32 v[44:45], v[42:43], v[50:51] op_sel_hi:[1,0]
	v_cvt_pk_bf16_f32 v42, v46, v47
	v_cvt_pk_bf16_f32 v43, v48, v49
	v_pk_mul_f32 v[40:41], v[40:41], v[50:51] op_sel_hi:[1,0]
	v_cvt_pk_bf16_f32 v44, v44, v45
	v_cvt_pk_bf16_f32 v45, v54, v55
	global_store_dwordx4 v[52:53], v[42:45], off
	v_pk_mul_f32 v[38:39], v[38:39], v[50:51] op_sel_hi:[1,0]
	s_nop 0
	v_pk_mul_f32 v[42:43], v[36:37], v[50:51] op_sel_hi:[1,0]
	v_pk_mul_f32 v[36:37], v[34:35], v[50:51] op_sel_hi:[1,0]
	v_cvt_pk_bf16_f32 v34, v38, v39
	v_cvt_pk_bf16_f32 v35, v40, v41
	v_add_u32_e32 v38, 0xa0, v148
	v_cvt_pk_bf16_f32 v36, v36, v37
	v_cvt_pk_bf16_f32 v37, v42, v43
	global_store_dwordx4 v[52:53], v[34:37], off offset:256
	ds_read_b128 v[34:37], v147 offset:1536
	v_ashrrev_i32_e32 v39, 31, v38
	v_mul_lo_u32 v42, s68, v39
	v_mul_lo_u32 v43, s69, v38
	v_mad_u64_u32 v[38:39], s[16:17], s68, v38, 0
	s_waitcnt lgkmcnt(0)
	v_mov_b32_e32 v40, v35
	v_mov_b32_e32 v41, v36
	v_mov_b32_e32 v35, v37
	v_pk_add_f32 v[34:35], v[40:41], v[34:35]
	v_add3_u32 v39, v39, v42, v43
	v_add_f32_e32 v34, v34, v35
	v_fmamk_f32 v34, v34, 0x3a800000, v155
	v_rsq_f32_e32 v34, v34
	v_lshl_add_u64 v[36:37], v[38:39], 1, s[78:79]
	v_lshl_add_u64 v[36:37], v[36:37], 0, v[140:141]
	v_pk_mul_f32 v[32:33], v[32:33], v[34:35] op_sel_hi:[1,0]
	v_pk_mul_f32 v[30:31], v[30:31], v[34:35] op_sel_hi:[1,0]
	v_pk_mul_f32 v[38:39], v[28:29], v[34:35] op_sel_hi:[1,0]
	v_pk_mul_f32 v[28:29], v[26:27], v[34:35] op_sel_hi:[1,0]
	v_cvt_pk_bf16_f32 v26, v30, v31
	v_cvt_pk_bf16_f32 v27, v32, v33
	v_pk_mul_f32 v[24:25], v[24:25], v[34:35] op_sel_hi:[1,0]
	v_cvt_pk_bf16_f32 v28, v28, v29
	v_cvt_pk_bf16_f32 v29, v38, v39
	global_store_dwordx4 v[36:37], v[26:29], off
	v_pk_mul_f32 v[22:23], v[22:23], v[34:35] op_sel_hi:[1,0]
	s_nop 0
	v_pk_mul_f32 v[26:27], v[20:21], v[34:35] op_sel_hi:[1,0]
	v_pk_mul_f32 v[20:21], v[18:19], v[34:35] op_sel_hi:[1,0]
	v_cvt_pk_bf16_f32 v18, v22, v23
	v_cvt_pk_bf16_f32 v19, v24, v25
	v_add_u32_e32 v22, 0xb0, v148
	v_cvt_pk_bf16_f32 v20, v20, v21
	v_cvt_pk_bf16_f32 v21, v26, v27
	global_store_dwordx4 v[36:37], v[18:21], off offset:256
	ds_read_b128 v[18:21], v147 offset:1792
	v_ashrrev_i32_e32 v23, 31, v22
	v_mul_lo_u32 v26, s68, v23
	v_mul_lo_u32 v27, s69, v22
	v_mad_u64_u32 v[22:23], s[16:17], s68, v22, 0
	s_waitcnt lgkmcnt(0)
	v_mov_b32_e32 v24, v19
	v_mov_b32_e32 v25, v20
	v_mov_b32_e32 v19, v21
	v_pk_add_f32 v[18:19], v[24:25], v[18:19]
	v_add3_u32 v23, v23, v26, v27
	v_add_f32_e32 v18, v18, v19
	v_fmamk_f32 v18, v18, 0x3a800000, v155
	v_rsq_f32_e32 v18, v18
	v_lshl_add_u64 v[20:21], v[22:23], 1, s[78:79]
	v_lshl_add_u64 v[20:21], v[20:21], 0, v[140:141]
	v_pk_mul_f32 v[16:17], v[16:17], v[18:19] op_sel_hi:[1,0]
	v_pk_mul_f32 v[14:15], v[14:15], v[18:19] op_sel_hi:[1,0]
	v_pk_mul_f32 v[22:23], v[12:13], v[18:19] op_sel_hi:[1,0]
	v_pk_mul_f32 v[12:13], v[10:11], v[18:19] op_sel_hi:[1,0]
	v_cvt_pk_bf16_f32 v10, v14, v15
	v_cvt_pk_bf16_f32 v11, v16, v17
	v_pk_mul_f32 v[8:9], v[8:9], v[18:19] op_sel_hi:[1,0]
	v_cvt_pk_bf16_f32 v12, v12, v13
	v_cvt_pk_bf16_f32 v13, v22, v23
	global_store_dwordx4 v[20:21], v[10:13], off
	v_pk_mul_f32 v[6:7], v[6:7], v[18:19] op_sel_hi:[1,0]
	s_nop 0
	v_pk_mul_f32 v[10:11], v[4:5], v[18:19] op_sel_hi:[1,0]
	v_pk_mul_f32 v[4:5], v[2:3], v[18:19] op_sel_hi:[1,0]
	v_cvt_pk_bf16_f32 v2, v6, v7
	v_cvt_pk_bf16_f32 v3, v8, v9
	s_nop 0
	v_cvt_pk_bf16_f32 v4, v4, v5
	v_cvt_pk_bf16_f32 v5, v10, v11
	global_store_dwordx4 v[20:21], v[2:5], off offset:256
	s_cbranch_vccnz .LBB0_410
	s_nop 0
	v_lshl_add_u32 v2, s61, 8, v145
	v_ashrrev_i32_e32 v3, 31, v2
	s_mov_b32 m0, s31
	v_lshl_add_u64 v[2:3], v[2:3], 4, s[96:97]
	global_load_lds_dwordx4 v[2:3], off
	v_lshl_add_u64 v[2:3], v[2:3], 0, s[82:83]
	s_add_i32 m0, s31, 0x400
	s_andn2_b64 vcc, exec, s[8:9]
	global_load_lds_dwordx4 v[2:3], off
	s_cbranch_vccnz .LBB0_409
	s_barrier
	s_branch .LBB0_409
